# baseline (speedup 1.0000x reference)
; template <int DQK, int MODE> ...
;     ...
;     for (int it = 0; it < ntile; it += 2) {
;       if (!step(R0, it)) break;
;       if (it + 1 < ntile) {
;         if (!step(R1, it + 1)) break;
;       }
;     }
.LBB0_989:
	s_add_i32 s3, s3, 2
	s_cmp_le_i32 s5, s2
	s_cbranch_scc0 .LBB0_1002

; template <int DQK, int MODE> ...
;     ...
;     for (int it = 0; it < ntile; it += 2) {
;       if (!step(R0, it)) break;
;       if (it + 1 < ntile) {
;         if (!step(R1, it + 1)) break;
;       }
;     }
.LBB0_2126:
	s_add_i32 s17, s17, 2
	s_cmp_le_i32 s18, s16
	s_cbranch_scc0 .LBB0_2139
